# SSD prompt step (3a): wave 0 publishes w_l = dt_l*exp(cs_last-cs_l) with the prefix sum; the 16 per-thread exponentials per chunk are gone
# speedup vs baseline: 1.0088x; 1.0088x over previous
.LBB0_846:
	s_and_saveexec_b64 s[78:79], s[4:5]
	s_cbranch_execz .LBB0_848
	s_waitcnt vmcnt(1)
	v_mul_f32_e64 v42, v95, -v184
	s_nop 1
	v_add_f32_dpp v42, v42, v42 row_shr:1 row_mask:0xf bank_mask:0xf
	s_nop 1
	v_add_f32_dpp v42, v42, v42 row_shr:2 row_mask:0xf bank_mask:0xf
	s_nop 1
	v_add_f32_dpp v42, v42, v42 row_shr:4 row_mask:0xf bank_mask:0xf
	s_nop 1
	v_add_f32_dpp v42, v42, v42 row_shr:8 row_mask:0xf bank_mask:0xf
	s_nop 1
	v_add_f32_dpp v42, v42, v42 row_bcast:15 row_mask:0xa bank_mask:0xf
	s_nop 1
	v_add_f32_dpp v42, v42, v42 row_bcast:31 row_mask:0xc bank_mask:0xf
	ds_write_b32 v65, v42
	ds_write_b32 v85, v95
	v_readlane_b32 s99, v42, 63
	s_nop 1
	v_sub_f32_e32 v43, s99, v42
	v_mul_f32_e32 v43, 0x3fb8aa3b, v43
	v_exp_f32_e32 v43, v43
	s_nop 0
	v_mul_f32_e32 v43, v95, v43
	ds_write_b32 v65, v43 offset:512

.LBB0_852:
	v_mov_b32_e32 v50, s87
	ds_read_b32 v187, v50
	ds_read_b128 v[42:45], v119 offset:512
	ds_read_b128 v[46:49], v121 offset:512
	ds_read_u16 v50, v165 offset:17408
	ds_read_u16 v51, v166 offset:17408
	ds_read_u16 v52, v166 offset:17680
	ds_read_u16 v53, v166 offset:17952
	ds_read_u16 v54, v166 offset:18224
	ds_read_u16 v55, v166 offset:18496
	ds_read_u16 v56, v166 offset:18768
	ds_read_u16 v57, v166 offset:19040
	ds_read_b128 v[192:195], v123 offset:512
	ds_read_b128 v[196:199], v125 offset:512
	s_waitcnt lgkmcnt(2)
	v_lshlrev_b32_e32 v50, 16, v50
	v_lshlrev_b32_e32 v51, 16, v51
	v_lshlrev_b32_e32 v52, 16, v52
	v_lshlrev_b32_e32 v53, 16, v53
	v_lshlrev_b32_e32 v54, 16, v54
	v_lshlrev_b32_e32 v55, 16, v55
	v_lshlrev_b32_e32 v56, 16, v56
	v_lshlrev_b32_e32 v57, 16, v57
	v_mul_f32_e32 v50, v42, v50
	v_mul_f32_e32 v51, v43, v51
	v_mul_f32_e32 v52, v44, v52
	v_mul_f32_e32 v53, v45, v53
	v_mul_f32_e32 v54, v46, v54
	v_mul_f32_e32 v55, v47, v55
	v_mul_f32_e32 v56, v48, v56
	v_mul_f32_e32 v57, v49, v57
	v_cvt_pk_bf16_f32 v42, v50, v51
	v_cvt_pk_bf16_f32 v43, v52, v53
	v_cvt_pk_bf16_f32 v44, v54, v55
	v_cvt_pk_bf16_f32 v45, v56, v57
	ds_write_b128 v106, v[42:45] offset:52224
	ds_read_u16 v50, v166 offset:19312
	ds_read_u16 v51, v166 offset:19584
	ds_read_u16 v52, v166 offset:19856
	ds_read_u16 v53, v166 offset:20128
	ds_read_u16 v54, v166 offset:20400
	ds_read_u16 v55, v166 offset:20672
	ds_read_u16 v56, v166 offset:20944
	ds_read_u16 v57, v166 offset:21216
	s_waitcnt lgkmcnt(0)
	v_lshlrev_b32_e32 v50, 16, v50
	v_lshlrev_b32_e32 v51, 16, v51
	v_lshlrev_b32_e32 v52, 16, v52
	v_lshlrev_b32_e32 v53, 16, v53
	v_lshlrev_b32_e32 v54, 16, v54
	v_lshlrev_b32_e32 v55, 16, v55
	v_lshlrev_b32_e32 v56, 16, v56
	v_lshlrev_b32_e32 v57, 16, v57
	v_mul_f32_e32 v50, v192, v50
	v_mul_f32_e32 v51, v193, v51
	v_mul_f32_e32 v52, v194, v52
	v_mul_f32_e32 v53, v195, v53
	v_mul_f32_e32 v54, v196, v54
	v_mul_f32_e32 v55, v197, v55
	v_mul_f32_e32 v56, v198, v56
	v_mul_f32_e32 v57, v199, v57
	v_cvt_pk_bf16_f32 v42, v50, v51
	v_cvt_pk_bf16_f32 v43, v52, v53
	v_cvt_pk_bf16_f32 v44, v54, v55
	v_cvt_pk_bf16_f32 v45, v56, v57
	ds_write_b128 v106, v[42:45] offset:52240
	v_mov_b32_e32 v48, 0
	v_mov_b32_e32 v42, 0
	v_mov_b32_e32 v43, 0
	v_mov_b32_e32 v44, 0
	v_mov_b32_e32 v45, 0
	s_and_saveexec_b64 s[78:79], s[20:21]
	s_cbranch_execz .LBB0_854
	ds_read_b128 v[42:45], v108
	ds_read_b128 v[50:53], v108 offset:64
	ds_read_b128 v[54:57], v182 offset:17408
	ds_read_b128 v[192:195], v182 offset:17472
	s_waitcnt lgkmcnt(1)
	v_mfma_f32_16x16x32_bf16 v[42:45], v[42:45], v[54:57], 0
	ds_read_b128 v[54:57], v108 offset:128
	ds_read_b128 v[196:199], v108 offset:192
	s_waitcnt lgkmcnt(2)
	v_mfma_f32_16x16x32_bf16 v[42:45], v[50:53], v[192:195], v[42:45]
	ds_read_b128 v[50:53], v182 offset:17536
	ds_read_b128 v[192:195], v182 offset:17600
	s_waitcnt lgkmcnt(1)
	v_mfma_f32_16x16x32_bf16 v[42:45], v[54:57], v[50:53], v[42:45]
	s_waitcnt lgkmcnt(0)
	v_mfma_f32_16x16x32_bf16 v[42:45], v[196:199], v[192:195], v[42:45]
